# v8: same as v7 but accumulator pairs visited n-major (consecutive pairs share the B-tile fragment operand); bit-exact
# speedup vs baseline: 1.0255x; 1.0074x over previous
; #define PG8_STAGE(bufoff, gbase, voff) do { _Pragma("unroll") for (int _i = 0; _i < 2; ++_i) \
;         __builtin_amdgcn_global_load_lds((const unsigned*)((const char*)(gbase) + (voff)[_i]), (LAS unsigned*)(lds + (bufoff) + ldsw + _i * 8192), 16, 0, 0); } while (0)
; #define PG8_LDA(dst, b, h) do { _Pragma("unroll") for (int m = 0; m < 4; ++m) _Pragma("unroll") for (int k = 0; k < 2; ++k) dst[m][k] = *(const LAS bf16x8*)(lds + PG8_SA(b, h) + aoff + m * 2048 + k * 1024); } while (0)
; #define PG8_LDB(dst, b, h) do { _Pragma("unroll") for (int n = 0; n < 2; ++n) _Pragma("unroll") for (int k = 0; k < 2; ++k) dst[n][k] = *(const LAS bf16x8*)(lds + PG8_SB(b, h) + boff + n * 2048 + k * 1024); } while (0)
; #define PG8_MMA(ai, bj, At, Bt) do { __builtin_amdgcn_s_setprio(3); _Pragma("unroll") for (int m = 0; m < 4; ++m) _Pragma("unroll") for (int n = 0; n < 2; ++n) _Pragma("unroll") for (int k = 0; k < 2; ++k) \
;         acc[ai][bj][m][n] = __builtin_amdgcn_mfma_f32_16x16x32_bf16(Bt[n][k], At[m][k], acc[ai][bj][m][n], 0, 0, 0); __builtin_amdgcn_s_setprio(0); } while (0)
; #define PG8_WAIT_V(n) asm volatile("s_waitcnt vmcnt(" #n ")" ::: "memory")
; #define PG8_WAIT_L(n) asm volatile("s_waitcnt lgkmcnt(" #n ")" ::: "memory")
; template <class Epi>
; __device__ __forceinline__ void gemm_phase(LAS unsigned char* lds, const Gemm g, const StaticOrder& S, const Epi& E, const int tid) {
;     ...
;                 for (int n = 0; n < 2; ++n) acc[a][b][m][n] = (f32x4){0.f, 0.f, 0.f, 0.f};
;     ...
;         for (int t = 0; t < nt; t += 2) {
;             const bool last = (t == nt - 2);
;             const char* a1 = cA + (size_t)(t + 1) * kstep;
;             const char* a2 = last ? nA : cA + (size_t)(t + 2) * kstep; const char* b2 = last ? nB : cB + (size_t)(t + 2) * kstep;
;             const char* a3 = a2 + kstep; const char* b3 = b2 + kstep;
;             PG8_LDB(B0, 0, 0); PG8_LDB(B1, 0, 1); PG8_SCHED; PG8_LDA(At, 0, 0); PG8_STAGE(PG8_SA(1, 1), a1 + hstepA, voffA);
;             PG8_WAIT_V(8); PG8_WAIT_L(0); PG8_BAR; PG8_MMA(0, 0, At, B0); PG8_MMA(0, 1, At, B1); PG8_BAR; PG8_SCHED;
;             PG8_LDA(At, 0, 1); PG8_STAGE(PG8_SB(0, 0), b2, voffB); PG8_STAGE(PG8_SB(0, 1), b2 + hstepB, voffB); PG8_STAGE(PG8_SA(0, 0), a2, voffA);
;             PG8_WAIT_V(8); PG8_WAIT_L(0); PG8_BAR; PG8_MMA(1, 0, At, B0); PG8_MMA(1, 1, At, B1); PG8_BAR; PG8_SCHED;
.LBB0_264:
	s_add_u32 s30, s6, 0x100
	s_addc_u32 s31, s7, 0
	s_add_u32 s4, s20, 0x80
	s_addc_u32 s5, s21, 0
	s_mov_b32 s6, 0
	s_add_i32 s20, s6, 2
	s_add_u32 s21, s4, 0x80
	s_addc_u32 s7, s5, 0
	s_add_i32 s55, 0, 0x10000
	s_cmp_eq_u32 s48, s6
	s_cselect_b32 s7, s79, s7
	s_cselect_b32 s6, s78, s21
	s_cselect_b32 vcc_hi, s81, s31
	s_cselect_b32 vcc_lo, s80, s30
	s_add_i32 s21, 0, 0x14000
	v_add_u32_e32 v152, s55, v169
	v_add_u32_e32 v156, s21, v169
	ds_read_b128 v[140:143], v152
	ds_read_b128 v[144:147], v152 offset:1024
	ds_read_b128 v[148:151], v152 offset:2048
	ds_read_b128 v[152:155], v152 offset:3072
	ds_read_b128 v[172:175], v156
	ds_read_b128 v[180:183], v156 offset:1024
	ds_read_b128 v[184:187], v156 offset:2048
	ds_read_b128 v[194:197], v156 offset:3072
	v_lshl_add_u64 v[156:157], s[4:5], 0, v[138:139]
	s_add_i32 m0, s94, 0xc000
	ds_read_b128 v[198:201], v171
	ds_read_b128 v[202:205], v171 offset:1024
	ds_read_b128 v[206:209], v171 offset:2048
	ds_read_b128 v[210:213], v171 offset:3072
	ds_read_b128 v[214:217], v171 offset:4096
	ds_read_b128 v[218:221], v171 offset:5120
	ds_read_b128 v[222:225], v171 offset:6144
	ds_read_b128 v[226:229], v171 offset:7168
	global_load_lds_dwordx4 v[156:157], off
	v_lshl_add_u64 v[156:157], s[4:5], 0, v[136:137]
	s_add_i32 m0, s94, 0xe000
	s_nop 0
	global_load_lds_dwordx4 v[156:157], off
	s_waitcnt vmcnt(8)
	s_waitcnt lgkmcnt(0)
	s_barrier
	s_setprio 3
	s_waitcnt lgkmcnt(0)
	v_mfma_f32_16x16x32_bf16 v[124:127], v[140:143], v[198:201], 0
	v_mfma_f32_16x16x32_bf16 v[124:127], v[144:147], v[202:205], v[124:127]
	v_mfma_f32_16x16x32_bf16 v[116:119], v[140:143], v[206:209], 0
	v_mfma_f32_16x16x32_bf16 v[116:119], v[144:147], v[210:213], v[116:119]
	v_mfma_f32_16x16x32_bf16 v[100:103], v[140:143], v[214:217], 0
	v_mfma_f32_16x16x32_bf16 v[100:103], v[144:147], v[218:221], v[100:103]
	v_mfma_f32_16x16x32_bf16 v[84:87], v[140:143], v[222:225], 0
	v_mfma_f32_16x16x32_bf16 v[84:87], v[144:147], v[226:229], v[84:87]
	v_mfma_f32_16x16x32_bf16 v[120:123], v[148:151], v[198:201], 0
	v_mfma_f32_16x16x32_bf16 v[120:123], v[152:155], v[202:205], v[120:123]
	v_mfma_f32_16x16x32_bf16 v[108:111], v[148:151], v[206:209], 0
	v_mfma_f32_16x16x32_bf16 v[108:111], v[152:155], v[210:213], v[108:111]
	v_mfma_f32_16x16x32_bf16 v[92:95], v[148:151], v[214:217], 0
	v_mfma_f32_16x16x32_bf16 v[92:95], v[152:155], v[218:221], v[92:95]
	v_mfma_f32_16x16x32_bf16 v[76:79], v[148:151], v[222:225], 0
	v_mfma_f32_16x16x32_bf16 v[76:79], v[152:155], v[226:229], v[76:79]
	s_setprio 0
	s_setprio 3
	v_mfma_f32_16x16x32_bf16 v[112:115], v[172:175], v[198:201], 0
	v_mfma_f32_16x16x32_bf16 v[112:115], v[180:183], v[202:205], v[112:115]
	v_mfma_f32_16x16x32_bf16 v[96:99], v[172:175], v[206:209], 0
	v_mfma_f32_16x16x32_bf16 v[96:99], v[180:183], v[210:213], v[96:99]
	v_mfma_f32_16x16x32_bf16 v[80:83], v[172:175], v[214:217], 0
	v_mfma_f32_16x16x32_bf16 v[80:83], v[180:183], v[218:221], v[80:83]
	v_mfma_f32_16x16x32_bf16 v[68:71], v[172:175], v[222:225], 0
	v_mfma_f32_16x16x32_bf16 v[68:71], v[180:183], v[226:229], v[68:71]
	v_mfma_f32_16x16x32_bf16 v[104:107], v[184:187], v[198:201], 0
	v_mfma_f32_16x16x32_bf16 v[104:107], v[194:197], v[202:205], v[104:107]
	v_mfma_f32_16x16x32_bf16 v[88:91], v[184:187], v[206:209], 0
	v_mfma_f32_16x16x32_bf16 v[88:91], v[194:197], v[210:213], v[88:91]
	v_mfma_f32_16x16x32_bf16 v[72:75], v[184:187], v[214:217], 0
	v_mfma_f32_16x16x32_bf16 v[72:75], v[194:197], v[218:221], v[72:75]
	v_mfma_f32_16x16x32_bf16 v[64:67], v[184:187], v[222:225], 0
	v_mfma_f32_16x16x32_bf16 v[64:67], v[194:197], v[226:229], v[64:67]
	s_setprio 0
	s_barrier
	s_add_i32 s55, s55, s93
	v_lshl_add_u64 v[156:157], vcc, 0, v[130:131]
	s_mov_b32 m0, s55
	ds_read_b128 v[198:201], v171 offset:16384
	ds_read_b128 v[202:205], v171 offset:17408
	ds_read_b128 v[206:209], v171 offset:18432
	ds_read_b128 v[210:213], v171 offset:19456
	ds_read_b128 v[214:217], v171 offset:20480
	ds_read_b128 v[218:221], v171 offset:21504
	ds_read_b128 v[222:225], v171 offset:22528
	ds_read_b128 v[226:229], v171 offset:23552
	global_load_lds_dwordx4 v[156:157], off
	s_add_i32 m0, s55, 0x2000
	v_lshl_add_u64 v[190:191], vcc, 0, v[134:135]
	s_add_u32 vcc_lo, vcc_lo, s91
	s_addc_u32 vcc_hi, vcc_hi, 0
	s_add_i32 s21, s21, s93
	global_load_lds_dwordx4 v[190:191], off
	v_lshl_add_u64 v[240:241], vcc, 0, v[130:131]
	s_mov_b32 m0, s21
	v_lshl_add_u64 v[242:243], vcc, 0, v[134:135]
	global_load_lds_dwordx4 v[240:241], off
	s_add_i32 m0, s21, 0x2000
	v_lshl_add_u64 v[244:245], s[6:7], 0, v[128:129]
	global_load_lds_dwordx4 v[242:243], off
	s_mov_b32 m0, s94
	v_lshl_add_u64 v[246:247], s[6:7], 0, v[132:133]
	global_load_lds_dwordx4 v[244:245], off
	s_mov_b32 m0, s95
	s_nop 0
	global_load_lds_dwordx4 v[246:247], off
	s_waitcnt vmcnt(8)
	s_waitcnt lgkmcnt(0)
	s_barrier
; #define PG8_STAGE(bufoff, gbase, voff) do { _Pragma("unroll") for (int _i = 0; _i < 2; ++_i) \
;         __builtin_amdgcn_global_load_lds((const unsigned*)((const char*)(gbase) + (voff)[_i]), (LAS unsigned*)(lds + (bufoff) + ldsw + _i * 8192), 16, 0, 0); } while (0)
; #define PG8_LDA(dst, b, h) do { _Pragma("unroll") for (int m = 0; m < 4; ++m) _Pragma("unroll") for (int k = 0; k < 2; ++k) dst[m][k] = *(const LAS bf16x8*)(lds + PG8_SA(b, h) + aoff + m * 2048 + k * 1024); } while (0)
; #define PG8_LDB(dst, b, h) do { _Pragma("unroll") for (int n = 0; n < 2; ++n) _Pragma("unroll") for (int k = 0; k < 2; ++k) dst[n][k] = *(const LAS bf16x8*)(lds + PG8_SB(b, h) + boff + n * 2048 + k * 1024); } while (0)
; #define PG8_MMA(ai, bj, At, Bt) do { __builtin_amdgcn_s_setprio(3); _Pragma("unroll") for (int m = 0; m < 4; ++m) _Pragma("unroll") for (int n = 0; n < 2; ++n) _Pragma("unroll") for (int k = 0; k < 2; ++k) \
;         acc[ai][bj][m][n] = __builtin_amdgcn_mfma_f32_16x16x32_bf16(Bt[n][k], At[m][k], acc[ai][bj][m][n], 0, 0, 0); __builtin_amdgcn_s_setprio(0); } while (0)
; #define PG8_WAIT_V(n) asm volatile("s_waitcnt vmcnt(" #n ")" ::: "memory")
; #define PG8_WAIT_L(n) asm volatile("s_waitcnt lgkmcnt(" #n ")" ::: "memory")
; #define PG8_BAR __builtin_amdgcn_s_barrier()
; #define PG8_SCHED __builtin_amdgcn_sched_barrier(0)
; template <class Epi>
; __device__ __forceinline__ void gemm_phase(LAS unsigned char* lds, const Gemm g, const StaticOrder& S, const Epi& E, const int tid) {
;     ...
;             PG8_WAIT_V(8); PG8_WAIT_L(0); PG8_BAR; PG8_MMA(1, 0, At, B0); PG8_MMA(1, 1, At, B1); PG8_BAR; PG8_SCHED;
;             PG8_LDB(B0, 1, 0); PG8_LDB(B1, 1, 1); PG8_SCHED; PG8_LDA(At, 1, 0); PG8_STAGE(PG8_SA(0, 1), a2 + hstepA, voffA);
;             PG8_WAIT_V(8); PG8_WAIT_L(0); PG8_BAR; PG8_MMA(0, 0, At, B0); PG8_MMA(0, 1, At, B1); PG8_BAR; PG8_SCHED;
	s_setprio 3
	s_waitcnt lgkmcnt(0)
	v_mfma_f32_16x16x32_bf16 v[60:63], v[140:143], v[198:201], 0
	v_mfma_f32_16x16x32_bf16 v[60:63], v[144:147], v[202:205], v[60:63]
	v_mfma_f32_16x16x32_bf16 v[48:51], v[140:143], v[206:209], 0
	v_mfma_f32_16x16x32_bf16 v[48:51], v[144:147], v[210:213], v[48:51]
	v_mfma_f32_16x16x32_bf16 v[32:35], v[140:143], v[214:217], 0
	v_mfma_f32_16x16x32_bf16 v[32:35], v[144:147], v[218:221], v[32:35]
	v_mfma_f32_16x16x32_bf16 v[16:19], v[140:143], v[222:225], 0
	v_mfma_f32_16x16x32_bf16 v[16:19], v[144:147], v[226:229], v[16:19]
	v_mfma_f32_16x16x32_bf16 v[56:59], v[148:151], v[198:201], 0
	v_mfma_f32_16x16x32_bf16 v[56:59], v[152:155], v[202:205], v[56:59]
	v_mfma_f32_16x16x32_bf16 v[40:43], v[148:151], v[206:209], 0
	v_mfma_f32_16x16x32_bf16 v[40:43], v[152:155], v[210:213], v[40:43]
	v_mfma_f32_16x16x32_bf16 v[24:27], v[148:151], v[214:217], 0
	v_mfma_f32_16x16x32_bf16 v[24:27], v[152:155], v[218:221], v[24:27]
	v_mfma_f32_16x16x32_bf16 v[8:11], v[148:151], v[222:225], 0
	v_mfma_f32_16x16x32_bf16 v[8:11], v[152:155], v[226:229], v[8:11]
	s_setprio 0
	s_setprio 3
	v_mfma_f32_16x16x32_bf16 v[52:55], v[172:175], v[198:201], 0
	v_mfma_f32_16x16x32_bf16 v[52:55], v[180:183], v[202:205], v[52:55]
	v_mfma_f32_16x16x32_bf16 v[36:39], v[172:175], v[206:209], 0
	v_mfma_f32_16x16x32_bf16 v[36:39], v[180:183], v[210:213], v[36:39]
	v_mfma_f32_16x16x32_bf16 v[20:23], v[172:175], v[214:217], 0
	v_mfma_f32_16x16x32_bf16 v[20:23], v[180:183], v[218:221], v[20:23]
	v_mfma_f32_16x16x32_bf16 v[4:7], v[172:175], v[222:225], 0
	v_mfma_f32_16x16x32_bf16 v[4:7], v[180:183], v[226:229], v[4:7]
	v_mfma_f32_16x16x32_bf16 v[44:47], v[184:187], v[198:201], 0
	v_mfma_f32_16x16x32_bf16 v[44:47], v[194:197], v[202:205], v[44:47]
	v_mfma_f32_16x16x32_bf16 v[28:31], v[184:187], v[206:209], 0
	v_mfma_f32_16x16x32_bf16 v[28:31], v[194:197], v[210:213], v[28:31]
	v_mfma_f32_16x16x32_bf16 v[12:15], v[184:187], v[214:217], 0
	v_mfma_f32_16x16x32_bf16 v[12:15], v[194:197], v[218:221], v[12:15]
	v_mfma_f32_16x16x32_bf16 v[0:3], v[184:187], v[222:225], 0
	v_mfma_f32_16x16x32_bf16 v[0:3], v[194:197], v[226:229], v[0:3]
	s_setprio 0
	s_barrier
	s_add_i32 s21, 0, 0x18000
	s_add_i32 s55, 0, 0x1c000
	v_add_u32_e32 v152, s21, v169
	v_add_u32_e32 v176, s55, v169
	ds_read_b128 v[140:143], v152
	ds_read_b128 v[144:147], v152 offset:1024
	ds_read_b128 v[148:151], v152 offset:2048
	ds_read_b128 v[152:155], v152 offset:3072
	ds_read_b128 v[172:175], v176
	ds_read_b128 v[180:183], v176 offset:1024
	ds_read_b128 v[184:187], v176 offset:2048
	ds_read_b128 v[194:197], v176 offset:3072
	s_add_u32 s6, s6, s26
	s_addc_u32 s7, s7, 0
	s_mov_b32 m0, s96
	v_lshl_add_u64 v[252:253], s[6:7], 0, v[128:129]
	ds_read_b128 v[198:201], v171 offset:32768
	ds_read_b128 v[202:205], v171 offset:33792
	ds_read_b128 v[206:209], v171 offset:34816
	ds_read_b128 v[210:213], v171 offset:35840
	ds_read_b128 v[214:217], v171 offset:36864
	ds_read_b128 v[218:221], v171 offset:37888
	ds_read_b128 v[222:225], v171 offset:38912
	ds_read_b128 v[226:229], v171 offset:39936
	global_load_lds_dwordx4 v[252:253], off
	v_lshl_add_u64 v[252:253], s[6:7], 0, v[132:133]
	s_mov_b32 m0, s97
	s_nop 0
	global_load_lds_dwordx4 v[252:253], off
	s_waitcnt vmcnt(8)
	s_waitcnt lgkmcnt(0)
	s_barrier
	s_setprio 3
	s_waitcnt lgkmcnt(0)
	v_mfma_f32_16x16x32_bf16 v[124:127], v[140:143], v[198:201], v[124:127]
	v_mfma_f32_16x16x32_bf16 v[124:127], v[144:147], v[202:205], v[124:127]
	v_mfma_f32_16x16x32_bf16 v[116:119], v[140:143], v[206:209], v[116:119]
	v_mfma_f32_16x16x32_bf16 v[116:119], v[144:147], v[210:213], v[116:119]
	v_mfma_f32_16x16x32_bf16 v[100:103], v[140:143], v[214:217], v[100:103]
	v_mfma_f32_16x16x32_bf16 v[100:103], v[144:147], v[218:221], v[100:103]
	v_mfma_f32_16x16x32_bf16 v[84:87], v[140:143], v[222:225], v[84:87]
	v_mfma_f32_16x16x32_bf16 v[84:87], v[144:147], v[226:229], v[84:87]
	v_mfma_f32_16x16x32_bf16 v[120:123], v[148:151], v[198:201], v[120:123]
	v_mfma_f32_16x16x32_bf16 v[120:123], v[152:155], v[202:205], v[120:123]
	v_mfma_f32_16x16x32_bf16 v[108:111], v[148:151], v[206:209], v[108:111]
	v_mfma_f32_16x16x32_bf16 v[108:111], v[152:155], v[210:213], v[108:111]
	v_mfma_f32_16x16x32_bf16 v[92:95], v[148:151], v[214:217], v[92:95]
	v_mfma_f32_16x16x32_bf16 v[92:95], v[152:155], v[218:221], v[92:95]
	v_mfma_f32_16x16x32_bf16 v[76:79], v[148:151], v[222:225], v[76:79]
	v_mfma_f32_16x16x32_bf16 v[76:79], v[152:155], v[226:229], v[76:79]
	s_setprio 0
	s_setprio 3
	v_mfma_f32_16x16x32_bf16 v[112:115], v[172:175], v[198:201], v[112:115]
	v_mfma_f32_16x16x32_bf16 v[112:115], v[180:183], v[202:205], v[112:115]
	v_mfma_f32_16x16x32_bf16 v[96:99], v[172:175], v[206:209], v[96:99]
	v_mfma_f32_16x16x32_bf16 v[96:99], v[180:183], v[210:213], v[96:99]
	v_mfma_f32_16x16x32_bf16 v[80:83], v[172:175], v[214:217], v[80:83]
	v_mfma_f32_16x16x32_bf16 v[80:83], v[180:183], v[218:221], v[80:83]
	v_mfma_f32_16x16x32_bf16 v[68:71], v[172:175], v[222:225], v[68:71]
	v_mfma_f32_16x16x32_bf16 v[68:71], v[180:183], v[226:229], v[68:71]
	v_mfma_f32_16x16x32_bf16 v[104:107], v[184:187], v[198:201], v[104:107]
	v_mfma_f32_16x16x32_bf16 v[104:107], v[194:197], v[202:205], v[104:107]
	v_mfma_f32_16x16x32_bf16 v[88:91], v[184:187], v[206:209], v[88:91]
	v_mfma_f32_16x16x32_bf16 v[88:91], v[194:197], v[210:213], v[88:91]
	v_mfma_f32_16x16x32_bf16 v[72:75], v[184:187], v[214:217], v[72:75]
	v_mfma_f32_16x16x32_bf16 v[72:75], v[194:197], v[218:221], v[72:75]
	v_mfma_f32_16x16x32_bf16 v[64:67], v[184:187], v[222:225], v[64:67]
	v_mfma_f32_16x16x32_bf16 v[64:67], v[194:197], v[226:229], v[64:67]
	s_setprio 0
	s_barrier
; #define PG8_STAGE(bufoff, gbase, voff) do { _Pragma("unroll") for (int _i = 0; _i < 2; ++_i) \
;         __builtin_amdgcn_global_load_lds((const unsigned*)((const char*)(gbase) + (voff)[_i]), (LAS unsigned*)(lds + (bufoff) + ldsw + _i * 8192), 16, 0, 0); } while (0)
; #define PG8_LDA(dst, b, h) do { _Pragma("unroll") for (int m = 0; m < 4; ++m) _Pragma("unroll") for (int k = 0; k < 2; ++k) dst[m][k] = *(const LAS bf16x8*)(lds + PG8_SA(b, h) + aoff + m * 2048 + k * 1024); } while (0)
; #define PG8_LDB(dst, b, h) do { _Pragma("unroll") for (int n = 0; n < 2; ++n) _Pragma("unroll") for (int k = 0; k < 2; ++k) dst[n][k] = *(const LAS bf16x8*)(lds + PG8_SB(b, h) + boff + n * 2048 + k * 1024); } while (0)
; #define PG8_MMA(ai, bj, At, Bt) do { __builtin_amdgcn_s_setprio(3); _Pragma("unroll") for (int m = 0; m < 4; ++m) _Pragma("unroll") for (int n = 0; n < 2; ++n) _Pragma("unroll") for (int k = 0; k < 2; ++k) \
;         acc[ai][bj][m][n] = __builtin_amdgcn_mfma_f32_16x16x32_bf16(Bt[n][k], At[m][k], acc[ai][bj][m][n], 0, 0, 0); __builtin_amdgcn_s_setprio(0); } while (0)
; #define PG8_WAIT_V(n) asm volatile("s_waitcnt vmcnt(" #n ")" ::: "memory")
; #define PG8_WAIT_L(n) asm volatile("s_waitcnt lgkmcnt(" #n ")" ::: "memory")
; #define PG8_BAR __builtin_amdgcn_s_barrier()
; #define PG8_SCHED __builtin_amdgcn_sched_barrier(0)
; template <class Epi>
; __device__ __forceinline__ void gemm_phase(LAS unsigned char* lds, const Gemm g, const StaticOrder& S, const Epi& E, const int tid) {
;     ...
;         for (int t = 0; t < nt; t += 2) {
;             const bool last = (t == nt - 2);
;             const char* a1 = cA + (size_t)(t + 1) * kstep;
;             const char* a2 = last ? nA : cA + (size_t)(t + 2) * kstep; const char* b2 = last ? nB : cB + (size_t)(t + 2) * kstep;
;             const char* a3 = a2 + kstep; const char* b3 = b2 + kstep;
;             PG8_LDB(B0, 0, 0); PG8_LDB(B1, 0, 1); PG8_SCHED; PG8_LDA(At, 0, 0); PG8_STAGE(PG8_SA(1, 1), a1 + hstepA, voffA);
;             PG8_WAIT_V(8); PG8_WAIT_L(0); PG8_BAR; PG8_MMA(0, 0, At, B0); PG8_MMA(0, 1, At, B1); PG8_BAR; PG8_SCHED;
;     ...
;             PG8_LDA(At, 1, 1); PG8_STAGE(PG8_SB(1, 0), b3, voffB); PG8_STAGE(PG8_SB(1, 1), b3 + hstepB, voffB); PG8_STAGE(PG8_SA(1, 0), a3, voffA);
;             PG8_WAIT_V(8); PG8_WAIT_L(0); PG8_BAR; PG8_MMA(1, 0, At, B0); PG8_MMA(1, 1, At, B1); PG8_BAR; PG8_SCHED;
	s_add_i32 s6, s21, s93
	v_lshl_add_u64 v[156:157], v[156:157], 0, s[22:23]
	s_mov_b32 m0, s6
	ds_read_b128 v[198:201], v171 offset:49152
	ds_read_b128 v[202:205], v171 offset:50176
	ds_read_b128 v[206:209], v171 offset:51200
	ds_read_b128 v[210:213], v171 offset:52224
	ds_read_b128 v[214:217], v171 offset:53248
	ds_read_b128 v[218:221], v171 offset:54272
	ds_read_b128 v[222:225], v171 offset:55296
	ds_read_b128 v[226:229], v171 offset:56320
	global_load_lds_dwordx4 v[156:157], off
	v_lshl_add_u64 v[156:157], v[190:191], 0, s[22:23]
	s_add_i32 m0, s6, 0x2000
	s_add_i32 s6, s55, s93
	global_load_lds_dwordx4 v[156:157], off
	v_lshl_add_u64 v[156:157], v[240:241], 0, s[22:23]
	s_mov_b32 m0, s6
	s_nop 0
	global_load_lds_dwordx4 v[156:157], off
	v_lshl_add_u64 v[156:157], v[242:243], 0, s[22:23]
	s_add_i32 m0, s6, 0x2000
	s_nop 0
	global_load_lds_dwordx4 v[156:157], off
	v_lshl_add_u64 v[156:157], v[244:245], 0, s[22:23]
	s_mov_b32 m0, s98
	s_nop 0
	global_load_lds_dwordx4 v[156:157], off
	v_lshl_add_u64 v[156:157], v[246:247], 0, s[22:23]
	s_mov_b32 m0, s99
	s_nop 0
	global_load_lds_dwordx4 v[156:157], off
	s_waitcnt vmcnt(8)
	s_waitcnt lgkmcnt(0)
	s_barrier
	s_setprio 3
	s_waitcnt lgkmcnt(0)
	v_mfma_f32_16x16x32_bf16 v[60:63], v[140:143], v[198:201], v[60:63]
	v_mfma_f32_16x16x32_bf16 v[60:63], v[144:147], v[202:205], v[60:63]
	v_mfma_f32_16x16x32_bf16 v[48:51], v[140:143], v[206:209], v[48:51]
	v_mfma_f32_16x16x32_bf16 v[48:51], v[144:147], v[210:213], v[48:51]
	v_mfma_f32_16x16x32_bf16 v[32:35], v[140:143], v[214:217], v[32:35]
	v_mfma_f32_16x16x32_bf16 v[32:35], v[144:147], v[218:221], v[32:35]
	v_mfma_f32_16x16x32_bf16 v[16:19], v[140:143], v[222:225], v[16:19]
	v_mfma_f32_16x16x32_bf16 v[16:19], v[144:147], v[226:229], v[16:19]
	v_mfma_f32_16x16x32_bf16 v[56:59], v[148:151], v[198:201], v[56:59]
	v_mfma_f32_16x16x32_bf16 v[56:59], v[152:155], v[202:205], v[56:59]
	v_mfma_f32_16x16x32_bf16 v[40:43], v[148:151], v[206:209], v[40:43]
	v_mfma_f32_16x16x32_bf16 v[40:43], v[152:155], v[210:213], v[40:43]
	v_mfma_f32_16x16x32_bf16 v[24:27], v[148:151], v[214:217], v[24:27]
	v_mfma_f32_16x16x32_bf16 v[24:27], v[152:155], v[218:221], v[24:27]
	v_mfma_f32_16x16x32_bf16 v[8:11], v[148:151], v[222:225], v[8:11]
	v_mfma_f32_16x16x32_bf16 v[8:11], v[152:155], v[226:229], v[8:11]
	s_setprio 0
	s_setprio 3
	v_mfma_f32_16x16x32_bf16 v[52:55], v[172:175], v[198:201], v[52:55]
	v_mfma_f32_16x16x32_bf16 v[52:55], v[180:183], v[202:205], v[52:55]
	v_mfma_f32_16x16x32_bf16 v[36:39], v[172:175], v[206:209], v[36:39]
	v_mfma_f32_16x16x32_bf16 v[36:39], v[180:183], v[210:213], v[36:39]
	v_mfma_f32_16x16x32_bf16 v[20:23], v[172:175], v[214:217], v[20:23]
	v_mfma_f32_16x16x32_bf16 v[20:23], v[180:183], v[218:221], v[20:23]
	v_mfma_f32_16x16x32_bf16 v[4:7], v[172:175], v[222:225], v[4:7]
	v_mfma_f32_16x16x32_bf16 v[4:7], v[180:183], v[226:229], v[4:7]
	v_mfma_f32_16x16x32_bf16 v[44:47], v[184:187], v[198:201], v[44:47]
	v_mfma_f32_16x16x32_bf16 v[44:47], v[194:197], v[202:205], v[44:47]
	v_mfma_f32_16x16x32_bf16 v[28:31], v[184:187], v[206:209], v[28:31]
	v_mfma_f32_16x16x32_bf16 v[28:31], v[194:197], v[210:213], v[28:31]
	v_mfma_f32_16x16x32_bf16 v[12:15], v[184:187], v[214:217], v[12:15]
	v_mfma_f32_16x16x32_bf16 v[12:15], v[194:197], v[218:221], v[12:15]
	v_mfma_f32_16x16x32_bf16 v[0:3], v[184:187], v[222:225], v[0:3]
	v_mfma_f32_16x16x32_bf16 v[0:3], v[194:197], v[226:229], v[0:3]
	s_setprio 0
	s_barrier
	s_add_u32 s30, s30, 0x100
	s_addc_u32 s31, s31, 0
	s_add_u32 s4, s4, 0x100
	s_addc_u32 s5, s5, 0
	s_cmp_ge_u32 s20, s89
	s_mov_b32 s6, s20
	s_cbranch_scc1 .Lpg_kloop_done
.LBB0_265:
	s_add_i32 s20, s6, 2
	s_add_u32 s21, s4, 0x80
	s_addc_u32 s7, s5, 0
	s_add_i32 s55, 0, 0x10000
	s_cmp_eq_u32 s48, s6
	s_cselect_b32 s7, s79, s7
	s_cselect_b32 s6, s78, s21
	s_cselect_b32 vcc_hi, s81, s31
	s_cselect_b32 vcc_lo, s80, s30
	s_add_i32 s21, 0, 0x14000
	v_add_u32_e32 v152, s55, v169
	v_add_u32_e32 v156, s21, v169
	ds_read_b128 v[140:143], v152
	ds_read_b128 v[144:147], v152 offset:1024
	ds_read_b128 v[148:151], v152 offset:2048
	ds_read_b128 v[152:155], v152 offset:3072
	ds_read_b128 v[172:175], v156
	ds_read_b128 v[180:183], v156 offset:1024
	ds_read_b128 v[184:187], v156 offset:2048
	ds_read_b128 v[194:197], v156 offset:3072
	v_lshl_add_u64 v[156:157], s[4:5], 0, v[138:139]
	s_add_i32 m0, s94, 0xc000
	ds_read_b128 v[198:201], v171
	ds_read_b128 v[202:205], v171 offset:1024
	ds_read_b128 v[206:209], v171 offset:2048
	ds_read_b128 v[210:213], v171 offset:3072
	ds_read_b128 v[214:217], v171 offset:4096
	ds_read_b128 v[218:221], v171 offset:5120
	ds_read_b128 v[222:225], v171 offset:6144
	ds_read_b128 v[226:229], v171 offset:7168
	global_load_lds_dwordx4 v[156:157], off
	v_lshl_add_u64 v[156:157], s[4:5], 0, v[136:137]
	s_add_i32 m0, s94, 0xe000
	s_nop 0
	global_load_lds_dwordx4 v[156:157], off
	s_waitcnt vmcnt(8)
	s_waitcnt lgkmcnt(0)
	s_barrier
; #define PG8_STAGE(bufoff, gbase, voff) do { _Pragma("unroll") for (int _i = 0; _i < 2; ++_i) \
;         __builtin_amdgcn_global_load_lds((const unsigned*)((const char*)(gbase) + (voff)[_i]), (LAS unsigned*)(lds + (bufoff) + ldsw + _i * 8192), 16, 0, 0); } while (0)
; #define PG8_LDA(dst, b, h) do { _Pragma("unroll") for (int m = 0; m < 4; ++m) _Pragma("unroll") for (int k = 0; k < 2; ++k) dst[m][k] = *(const LAS bf16x8*)(lds + PG8_SA(b, h) + aoff + m * 2048 + k * 1024); } while (0)
; #define PG8_LDB(dst, b, h) do { _Pragma("unroll") for (int n = 0; n < 2; ++n) _Pragma("unroll") for (int k = 0; k < 2; ++k) dst[n][k] = *(const LAS bf16x8*)(lds + PG8_SB(b, h) + boff + n * 2048 + k * 1024); } while (0)
; #define PG8_MMA(ai, bj, At, Bt) do { __builtin_amdgcn_s_setprio(3); _Pragma("unroll") for (int m = 0; m < 4; ++m) _Pragma("unroll") for (int n = 0; n < 2; ++n) _Pragma("unroll") for (int k = 0; k < 2; ++k) \
;         acc[ai][bj][m][n] = __builtin_amdgcn_mfma_f32_16x16x32_bf16(Bt[n][k], At[m][k], acc[ai][bj][m][n], 0, 0, 0); __builtin_amdgcn_s_setprio(0); } while (0)
; #define PG8_WAIT_V(n) asm volatile("s_waitcnt vmcnt(" #n ")" ::: "memory")
; #define PG8_WAIT_L(n) asm volatile("s_waitcnt lgkmcnt(" #n ")" ::: "memory")
; #define PG8_BAR __builtin_amdgcn_s_barrier()
; #define PG8_SCHED __builtin_amdgcn_sched_barrier(0)
; template <class Epi>
; __device__ __forceinline__ void gemm_phase(LAS unsigned char* lds, const Gemm g, const StaticOrder& S, const Epi& E, const int tid) {
;     ...
;             PG8_LDB(B0, 0, 0); PG8_LDB(B1, 0, 1); PG8_SCHED; PG8_LDA(At, 0, 0); PG8_STAGE(PG8_SA(1, 1), a1 + hstepA, voffA);
;             PG8_WAIT_V(8); PG8_WAIT_L(0); PG8_BAR; PG8_MMA(0, 0, At, B0); PG8_MMA(0, 1, At, B1); PG8_BAR; PG8_SCHED;
;             PG8_LDA(At, 0, 1); PG8_STAGE(PG8_SB(0, 0), b2, voffB); PG8_STAGE(PG8_SB(0, 1), b2 + hstepB, voffB); PG8_STAGE(PG8_SA(0, 0), a2, voffA);
;             PG8_WAIT_V(8); PG8_WAIT_L(0); PG8_BAR; PG8_MMA(1, 0, At, B0); PG8_MMA(1, 1, At, B1); PG8_BAR; PG8_SCHED;
	s_setprio 3
	s_waitcnt lgkmcnt(0)
	v_mfma_f32_16x16x32_bf16 v[124:127], v[140:143], v[198:201], v[124:127]
	v_mfma_f32_16x16x32_bf16 v[124:127], v[144:147], v[202:205], v[124:127]
	v_mfma_f32_16x16x32_bf16 v[116:119], v[140:143], v[206:209], v[116:119]
	v_mfma_f32_16x16x32_bf16 v[116:119], v[144:147], v[210:213], v[116:119]
	v_mfma_f32_16x16x32_bf16 v[100:103], v[140:143], v[214:217], v[100:103]
	v_mfma_f32_16x16x32_bf16 v[100:103], v[144:147], v[218:221], v[100:103]
	v_mfma_f32_16x16x32_bf16 v[84:87], v[140:143], v[222:225], v[84:87]
	v_mfma_f32_16x16x32_bf16 v[84:87], v[144:147], v[226:229], v[84:87]
	v_mfma_f32_16x16x32_bf16 v[120:123], v[148:151], v[198:201], v[120:123]
	v_mfma_f32_16x16x32_bf16 v[120:123], v[152:155], v[202:205], v[120:123]
	v_mfma_f32_16x16x32_bf16 v[108:111], v[148:151], v[206:209], v[108:111]
	v_mfma_f32_16x16x32_bf16 v[108:111], v[152:155], v[210:213], v[108:111]
	v_mfma_f32_16x16x32_bf16 v[92:95], v[148:151], v[214:217], v[92:95]
	v_mfma_f32_16x16x32_bf16 v[92:95], v[152:155], v[218:221], v[92:95]
	v_mfma_f32_16x16x32_bf16 v[76:79], v[148:151], v[222:225], v[76:79]
	v_mfma_f32_16x16x32_bf16 v[76:79], v[152:155], v[226:229], v[76:79]
	s_setprio 0
	s_setprio 3
	v_mfma_f32_16x16x32_bf16 v[112:115], v[172:175], v[198:201], v[112:115]
	v_mfma_f32_16x16x32_bf16 v[112:115], v[180:183], v[202:205], v[112:115]
	v_mfma_f32_16x16x32_bf16 v[96:99], v[172:175], v[206:209], v[96:99]
	v_mfma_f32_16x16x32_bf16 v[96:99], v[180:183], v[210:213], v[96:99]
	v_mfma_f32_16x16x32_bf16 v[80:83], v[172:175], v[214:217], v[80:83]
	v_mfma_f32_16x16x32_bf16 v[80:83], v[180:183], v[218:221], v[80:83]
	v_mfma_f32_16x16x32_bf16 v[68:71], v[172:175], v[222:225], v[68:71]
	v_mfma_f32_16x16x32_bf16 v[68:71], v[180:183], v[226:229], v[68:71]
	v_mfma_f32_16x16x32_bf16 v[104:107], v[184:187], v[198:201], v[104:107]
	v_mfma_f32_16x16x32_bf16 v[104:107], v[194:197], v[202:205], v[104:107]
	v_mfma_f32_16x16x32_bf16 v[88:91], v[184:187], v[206:209], v[88:91]
	v_mfma_f32_16x16x32_bf16 v[88:91], v[194:197], v[210:213], v[88:91]
	v_mfma_f32_16x16x32_bf16 v[72:75], v[184:187], v[214:217], v[72:75]
	v_mfma_f32_16x16x32_bf16 v[72:75], v[194:197], v[218:221], v[72:75]
	v_mfma_f32_16x16x32_bf16 v[64:67], v[184:187], v[222:225], v[64:67]
	v_mfma_f32_16x16x32_bf16 v[64:67], v[194:197], v[226:229], v[64:67]
	s_setprio 0
	s_barrier
	s_add_i32 s55, s55, s93
	v_lshl_add_u64 v[156:157], vcc, 0, v[130:131]
	s_mov_b32 m0, s55
	ds_read_b128 v[198:201], v171 offset:16384
	ds_read_b128 v[202:205], v171 offset:17408
	ds_read_b128 v[206:209], v171 offset:18432
	ds_read_b128 v[210:213], v171 offset:19456
	ds_read_b128 v[214:217], v171 offset:20480
	ds_read_b128 v[218:221], v171 offset:21504
	ds_read_b128 v[222:225], v171 offset:22528
	ds_read_b128 v[226:229], v171 offset:23552
	global_load_lds_dwordx4 v[156:157], off
	s_add_i32 m0, s55, 0x2000
	v_lshl_add_u64 v[190:191], vcc, 0, v[134:135]
	s_add_u32 vcc_lo, vcc_lo, s91
	s_addc_u32 vcc_hi, vcc_hi, 0
	s_add_i32 s21, s21, s93
	global_load_lds_dwordx4 v[190:191], off
	v_lshl_add_u64 v[240:241], vcc, 0, v[130:131]
	s_mov_b32 m0, s21
	v_lshl_add_u64 v[242:243], vcc, 0, v[134:135]
	global_load_lds_dwordx4 v[240:241], off
	s_add_i32 m0, s21, 0x2000
	v_lshl_add_u64 v[244:245], s[6:7], 0, v[128:129]
	global_load_lds_dwordx4 v[242:243], off
	s_mov_b32 m0, s94
	v_lshl_add_u64 v[246:247], s[6:7], 0, v[132:133]
	global_load_lds_dwordx4 v[244:245], off
	s_mov_b32 m0, s95
	s_nop 0
	global_load_lds_dwordx4 v[246:247], off
	s_waitcnt vmcnt(8)
	s_waitcnt lgkmcnt(0)
	s_barrier
	s_setprio 3
	s_waitcnt lgkmcnt(0)
	v_mfma_f32_16x16x32_bf16 v[60:63], v[140:143], v[198:201], v[60:63]
	v_mfma_f32_16x16x32_bf16 v[60:63], v[144:147], v[202:205], v[60:63]
	v_mfma_f32_16x16x32_bf16 v[48:51], v[140:143], v[206:209], v[48:51]
	v_mfma_f32_16x16x32_bf16 v[48:51], v[144:147], v[210:213], v[48:51]
	v_mfma_f32_16x16x32_bf16 v[32:35], v[140:143], v[214:217], v[32:35]
	v_mfma_f32_16x16x32_bf16 v[32:35], v[144:147], v[218:221], v[32:35]
	v_mfma_f32_16x16x32_bf16 v[16:19], v[140:143], v[222:225], v[16:19]
	v_mfma_f32_16x16x32_bf16 v[16:19], v[144:147], v[226:229], v[16:19]
	v_mfma_f32_16x16x32_bf16 v[56:59], v[148:151], v[198:201], v[56:59]
	v_mfma_f32_16x16x32_bf16 v[56:59], v[152:155], v[202:205], v[56:59]
	v_mfma_f32_16x16x32_bf16 v[40:43], v[148:151], v[206:209], v[40:43]
	v_mfma_f32_16x16x32_bf16 v[40:43], v[152:155], v[210:213], v[40:43]
	v_mfma_f32_16x16x32_bf16 v[24:27], v[148:151], v[214:217], v[24:27]
	v_mfma_f32_16x16x32_bf16 v[24:27], v[152:155], v[218:221], v[24:27]
	v_mfma_f32_16x16x32_bf16 v[8:11], v[148:151], v[222:225], v[8:11]
	v_mfma_f32_16x16x32_bf16 v[8:11], v[152:155], v[226:229], v[8:11]
	s_setprio 0
	s_setprio 3
	v_mfma_f32_16x16x32_bf16 v[52:55], v[172:175], v[198:201], v[52:55]
	v_mfma_f32_16x16x32_bf16 v[52:55], v[180:183], v[202:205], v[52:55]
	v_mfma_f32_16x16x32_bf16 v[36:39], v[172:175], v[206:209], v[36:39]
	v_mfma_f32_16x16x32_bf16 v[36:39], v[180:183], v[210:213], v[36:39]
	v_mfma_f32_16x16x32_bf16 v[20:23], v[172:175], v[214:217], v[20:23]
	v_mfma_f32_16x16x32_bf16 v[20:23], v[180:183], v[218:221], v[20:23]
	v_mfma_f32_16x16x32_bf16 v[4:7], v[172:175], v[222:225], v[4:7]
	v_mfma_f32_16x16x32_bf16 v[4:7], v[180:183], v[226:229], v[4:7]
	v_mfma_f32_16x16x32_bf16 v[44:47], v[184:187], v[198:201], v[44:47]
	v_mfma_f32_16x16x32_bf16 v[44:47], v[194:197], v[202:205], v[44:47]
	v_mfma_f32_16x16x32_bf16 v[28:31], v[184:187], v[206:209], v[28:31]
	v_mfma_f32_16x16x32_bf16 v[28:31], v[194:197], v[210:213], v[28:31]
	v_mfma_f32_16x16x32_bf16 v[12:15], v[184:187], v[214:217], v[12:15]
	v_mfma_f32_16x16x32_bf16 v[12:15], v[194:197], v[218:221], v[12:15]
	v_mfma_f32_16x16x32_bf16 v[0:3], v[184:187], v[222:225], v[0:3]
	v_mfma_f32_16x16x32_bf16 v[0:3], v[194:197], v[226:229], v[0:3]
	s_setprio 0
	s_barrier
; #define PG8_STAGE(bufoff, gbase, voff) do { _Pragma("unroll") for (int _i = 0; _i < 2; ++_i) \
;         __builtin_amdgcn_global_load_lds((const unsigned*)((const char*)(gbase) + (voff)[_i]), (LAS unsigned*)(lds + (bufoff) + ldsw + _i * 8192), 16, 0, 0); } while (0)
; #define PG8_LDA(dst, b, h) do { _Pragma("unroll") for (int m = 0; m < 4; ++m) _Pragma("unroll") for (int k = 0; k < 2; ++k) dst[m][k] = *(const LAS bf16x8*)(lds + PG8_SA(b, h) + aoff + m * 2048 + k * 1024); } while (0)
; #define PG8_LDB(dst, b, h) do { _Pragma("unroll") for (int n = 0; n < 2; ++n) _Pragma("unroll") for (int k = 0; k < 2; ++k) dst[n][k] = *(const LAS bf16x8*)(lds + PG8_SB(b, h) + boff + n * 2048 + k * 1024); } while (0)
; #define PG8_MMA(ai, bj, At, Bt) do { __builtin_amdgcn_s_setprio(3); _Pragma("unroll") for (int m = 0; m < 4; ++m) _Pragma("unroll") for (int n = 0; n < 2; ++n) _Pragma("unroll") for (int k = 0; k < 2; ++k) \
;         acc[ai][bj][m][n] = __builtin_amdgcn_mfma_f32_16x16x32_bf16(Bt[n][k], At[m][k], acc[ai][bj][m][n], 0, 0, 0); __builtin_amdgcn_s_setprio(0); } while (0)
; #define PG8_WAIT_V(n) asm volatile("s_waitcnt vmcnt(" #n ")" ::: "memory")
; #define PG8_WAIT_L(n) asm volatile("s_waitcnt lgkmcnt(" #n ")" ::: "memory")
; #define PG8_BAR __builtin_amdgcn_s_barrier()
; #define PG8_SCHED __builtin_amdgcn_sched_barrier(0)
; template <class Epi>
; __device__ __forceinline__ void gemm_phase(LAS unsigned char* lds, const Gemm g, const StaticOrder& S, const Epi& E, const int tid) {
;     ...
;             PG8_LDB(B0, 1, 0); PG8_LDB(B1, 1, 1); PG8_SCHED; PG8_LDA(At, 1, 0); PG8_STAGE(PG8_SA(0, 1), a2 + hstepA, voffA);
;             PG8_WAIT_V(8); PG8_WAIT_L(0); PG8_BAR; PG8_MMA(0, 0, At, B0); PG8_MMA(0, 1, At, B1); PG8_BAR; PG8_SCHED;
	s_add_i32 s21, 0, 0x18000
	s_add_i32 s55, 0, 0x1c000
	v_add_u32_e32 v152, s21, v169
	v_add_u32_e32 v176, s55, v169
	ds_read_b128 v[140:143], v152
	ds_read_b128 v[144:147], v152 offset:1024
	ds_read_b128 v[148:151], v152 offset:2048
	ds_read_b128 v[152:155], v152 offset:3072
	ds_read_b128 v[172:175], v176
	ds_read_b128 v[180:183], v176 offset:1024
	ds_read_b128 v[184:187], v176 offset:2048
	ds_read_b128 v[194:197], v176 offset:3072
	s_add_u32 s6, s6, s26
	s_addc_u32 s7, s7, 0
	s_mov_b32 m0, s96
	v_lshl_add_u64 v[252:253], s[6:7], 0, v[128:129]
	ds_read_b128 v[198:201], v171 offset:32768
	ds_read_b128 v[202:205], v171 offset:33792
	ds_read_b128 v[206:209], v171 offset:34816
	ds_read_b128 v[210:213], v171 offset:35840
	ds_read_b128 v[214:217], v171 offset:36864
	ds_read_b128 v[218:221], v171 offset:37888
	ds_read_b128 v[222:225], v171 offset:38912
	ds_read_b128 v[226:229], v171 offset:39936
	global_load_lds_dwordx4 v[252:253], off
	v_lshl_add_u64 v[252:253], s[6:7], 0, v[132:133]
	s_mov_b32 m0, s97
	s_nop 0
	global_load_lds_dwordx4 v[252:253], off
	s_waitcnt vmcnt(8)
	s_waitcnt lgkmcnt(0)
	s_barrier
	s_setprio 3
	s_waitcnt lgkmcnt(0)
	v_mfma_f32_16x16x32_bf16 v[124:127], v[140:143], v[198:201], v[124:127]
	v_mfma_f32_16x16x32_bf16 v[124:127], v[144:147], v[202:205], v[124:127]
	v_mfma_f32_16x16x32_bf16 v[116:119], v[140:143], v[206:209], v[116:119]
	v_mfma_f32_16x16x32_bf16 v[116:119], v[144:147], v[210:213], v[116:119]
	v_mfma_f32_16x16x32_bf16 v[100:103], v[140:143], v[214:217], v[100:103]
	v_mfma_f32_16x16x32_bf16 v[100:103], v[144:147], v[218:221], v[100:103]
	v_mfma_f32_16x16x32_bf16 v[84:87], v[140:143], v[222:225], v[84:87]
	v_mfma_f32_16x16x32_bf16 v[84:87], v[144:147], v[226:229], v[84:87]
	v_mfma_f32_16x16x32_bf16 v[120:123], v[148:151], v[198:201], v[120:123]
	v_mfma_f32_16x16x32_bf16 v[120:123], v[152:155], v[202:205], v[120:123]
	v_mfma_f32_16x16x32_bf16 v[108:111], v[148:151], v[206:209], v[108:111]
	v_mfma_f32_16x16x32_bf16 v[108:111], v[152:155], v[210:213], v[108:111]
	v_mfma_f32_16x16x32_bf16 v[92:95], v[148:151], v[214:217], v[92:95]
	v_mfma_f32_16x16x32_bf16 v[92:95], v[152:155], v[218:221], v[92:95]
	v_mfma_f32_16x16x32_bf16 v[76:79], v[148:151], v[222:225], v[76:79]
	v_mfma_f32_16x16x32_bf16 v[76:79], v[152:155], v[226:229], v[76:79]
	s_setprio 0
	s_setprio 3
	v_mfma_f32_16x16x32_bf16 v[112:115], v[172:175], v[198:201], v[112:115]
	v_mfma_f32_16x16x32_bf16 v[112:115], v[180:183], v[202:205], v[112:115]
	v_mfma_f32_16x16x32_bf16 v[96:99], v[172:175], v[206:209], v[96:99]
	v_mfma_f32_16x16x32_bf16 v[96:99], v[180:183], v[210:213], v[96:99]
	v_mfma_f32_16x16x32_bf16 v[80:83], v[172:175], v[214:217], v[80:83]
	v_mfma_f32_16x16x32_bf16 v[80:83], v[180:183], v[218:221], v[80:83]
	v_mfma_f32_16x16x32_bf16 v[68:71], v[172:175], v[222:225], v[68:71]
	v_mfma_f32_16x16x32_bf16 v[68:71], v[180:183], v[226:229], v[68:71]
	v_mfma_f32_16x16x32_bf16 v[104:107], v[184:187], v[198:201], v[104:107]
	v_mfma_f32_16x16x32_bf16 v[104:107], v[194:197], v[202:205], v[104:107]
	v_mfma_f32_16x16x32_bf16 v[88:91], v[184:187], v[206:209], v[88:91]
	v_mfma_f32_16x16x32_bf16 v[88:91], v[194:197], v[210:213], v[88:91]
	v_mfma_f32_16x16x32_bf16 v[72:75], v[184:187], v[214:217], v[72:75]
	v_mfma_f32_16x16x32_bf16 v[72:75], v[194:197], v[218:221], v[72:75]
	v_mfma_f32_16x16x32_bf16 v[64:67], v[184:187], v[222:225], v[64:67]
	v_mfma_f32_16x16x32_bf16 v[64:67], v[194:197], v[226:229], v[64:67]
	s_setprio 0
	s_barrier
; #define PG8_STAGE(bufoff, gbase, voff) do { _Pragma("unroll") for (int _i = 0; _i < 2; ++_i) \
;         __builtin_amdgcn_global_load_lds((const unsigned*)((const char*)(gbase) + (voff)[_i]), (LAS unsigned*)(lds + (bufoff) + ldsw + _i * 8192), 16, 0, 0); } while (0)
; #define PG8_LDA(dst, b, h) do { _Pragma("unroll") for (int m = 0; m < 4; ++m) _Pragma("unroll") for (int k = 0; k < 2; ++k) dst[m][k] = *(const LAS bf16x8*)(lds + PG8_SA(b, h) + aoff + m * 2048 + k * 1024); } while (0)
; #define PG8_MMA(ai, bj, At, Bt) do { __builtin_amdgcn_s_setprio(3); _Pragma("unroll") for (int m = 0; m < 4; ++m) _Pragma("unroll") for (int n = 0; n < 2; ++n) _Pragma("unroll") for (int k = 0; k < 2; ++k) \
;         acc[ai][bj][m][n] = __builtin_amdgcn_mfma_f32_16x16x32_bf16(Bt[n][k], At[m][k], acc[ai][bj][m][n], 0, 0, 0); __builtin_amdgcn_s_setprio(0); } while (0)
; #define PG8_WAIT_V(n) asm volatile("s_waitcnt vmcnt(" #n ")" ::: "memory")
; #define PG8_WAIT_L(n) asm volatile("s_waitcnt lgkmcnt(" #n ")" ::: "memory")
; #define PG8_BAR __builtin_amdgcn_s_barrier()
; #define PG8_SCHED __builtin_amdgcn_sched_barrier(0)
; template <class Epi>
; __device__ __forceinline__ void gemm_phase(LAS unsigned char* lds, const Gemm g, const StaticOrder& S, const Epi& E, const int tid) {
;     ...
;         for (int t = 0; t < nt; t += 2) {
;     ...
;             PG8_LDA(At, 1, 1); PG8_STAGE(PG8_SB(1, 0), b3, voffB); PG8_STAGE(PG8_SB(1, 1), b3 + hstepB, voffB); PG8_STAGE(PG8_SA(1, 0), a3, voffA);
;             PG8_WAIT_V(8); PG8_WAIT_L(0); PG8_BAR; PG8_MMA(1, 0, At, B0); PG8_MMA(1, 1, At, B1); PG8_BAR; PG8_SCHED;
	s_add_i32 s6, s21, s93
	v_lshl_add_u64 v[156:157], v[156:157], 0, s[22:23]
	s_mov_b32 m0, s6
	ds_read_b128 v[198:201], v171 offset:49152
	ds_read_b128 v[202:205], v171 offset:50176
	ds_read_b128 v[206:209], v171 offset:51200
	ds_read_b128 v[210:213], v171 offset:52224
	ds_read_b128 v[214:217], v171 offset:53248
	ds_read_b128 v[218:221], v171 offset:54272
	ds_read_b128 v[222:225], v171 offset:55296
	ds_read_b128 v[226:229], v171 offset:56320
	global_load_lds_dwordx4 v[156:157], off
	v_lshl_add_u64 v[156:157], v[190:191], 0, s[22:23]
	s_add_i32 m0, s6, 0x2000
	s_add_i32 s6, s55, s93
	global_load_lds_dwordx4 v[156:157], off
	v_lshl_add_u64 v[156:157], v[240:241], 0, s[22:23]
	s_mov_b32 m0, s6
	s_nop 0
	global_load_lds_dwordx4 v[156:157], off
	v_lshl_add_u64 v[156:157], v[242:243], 0, s[22:23]
	s_add_i32 m0, s6, 0x2000
	s_nop 0
	global_load_lds_dwordx4 v[156:157], off
	v_lshl_add_u64 v[156:157], v[244:245], 0, s[22:23]
	s_mov_b32 m0, s98
	s_nop 0
	global_load_lds_dwordx4 v[156:157], off
	v_lshl_add_u64 v[156:157], v[246:247], 0, s[22:23]
	s_mov_b32 m0, s99
	s_nop 0
	global_load_lds_dwordx4 v[156:157], off
	s_waitcnt vmcnt(8)
	s_waitcnt lgkmcnt(0)
	s_barrier
	s_setprio 3
	s_waitcnt lgkmcnt(0)
	v_mfma_f32_16x16x32_bf16 v[60:63], v[140:143], v[198:201], v[60:63]
	v_mfma_f32_16x16x32_bf16 v[60:63], v[144:147], v[202:205], v[60:63]
	v_mfma_f32_16x16x32_bf16 v[48:51], v[140:143], v[206:209], v[48:51]
	v_mfma_f32_16x16x32_bf16 v[48:51], v[144:147], v[210:213], v[48:51]
	v_mfma_f32_16x16x32_bf16 v[32:35], v[140:143], v[214:217], v[32:35]
	v_mfma_f32_16x16x32_bf16 v[32:35], v[144:147], v[218:221], v[32:35]
	v_mfma_f32_16x16x32_bf16 v[16:19], v[140:143], v[222:225], v[16:19]
	v_mfma_f32_16x16x32_bf16 v[16:19], v[144:147], v[226:229], v[16:19]
	v_mfma_f32_16x16x32_bf16 v[56:59], v[148:151], v[198:201], v[56:59]
	v_mfma_f32_16x16x32_bf16 v[56:59], v[152:155], v[202:205], v[56:59]
	v_mfma_f32_16x16x32_bf16 v[40:43], v[148:151], v[206:209], v[40:43]
	v_mfma_f32_16x16x32_bf16 v[40:43], v[152:155], v[210:213], v[40:43]
	v_mfma_f32_16x16x32_bf16 v[24:27], v[148:151], v[214:217], v[24:27]
	v_mfma_f32_16x16x32_bf16 v[24:27], v[152:155], v[218:221], v[24:27]
	v_mfma_f32_16x16x32_bf16 v[8:11], v[148:151], v[222:225], v[8:11]
	v_mfma_f32_16x16x32_bf16 v[8:11], v[152:155], v[226:229], v[8:11]
	s_setprio 0
	s_setprio 3
	v_mfma_f32_16x16x32_bf16 v[52:55], v[172:175], v[198:201], v[52:55]
	v_mfma_f32_16x16x32_bf16 v[52:55], v[180:183], v[202:205], v[52:55]
	v_mfma_f32_16x16x32_bf16 v[36:39], v[172:175], v[206:209], v[36:39]
	v_mfma_f32_16x16x32_bf16 v[36:39], v[180:183], v[210:213], v[36:39]
	v_mfma_f32_16x16x32_bf16 v[20:23], v[172:175], v[214:217], v[20:23]
	v_mfma_f32_16x16x32_bf16 v[20:23], v[180:183], v[218:221], v[20:23]
	v_mfma_f32_16x16x32_bf16 v[4:7], v[172:175], v[222:225], v[4:7]
	v_mfma_f32_16x16x32_bf16 v[4:7], v[180:183], v[226:229], v[4:7]
	v_mfma_f32_16x16x32_bf16 v[44:47], v[184:187], v[198:201], v[44:47]
	v_mfma_f32_16x16x32_bf16 v[44:47], v[194:197], v[202:205], v[44:47]
	v_mfma_f32_16x16x32_bf16 v[28:31], v[184:187], v[206:209], v[28:31]
	v_mfma_f32_16x16x32_bf16 v[28:31], v[194:197], v[210:213], v[28:31]
	v_mfma_f32_16x16x32_bf16 v[12:15], v[184:187], v[214:217], v[12:15]
	v_mfma_f32_16x16x32_bf16 v[12:15], v[194:197], v[218:221], v[12:15]
	v_mfma_f32_16x16x32_bf16 v[0:3], v[184:187], v[222:225], v[0:3]
	v_mfma_f32_16x16x32_bf16 v[0:3], v[194:197], v[226:229], v[0:3]
	s_setprio 0
	s_barrier
	s_add_u32 s30, s30, 0x100
	s_addc_u32 s31, s31, 0
	s_add_u32 s4, s4, 0x100
	s_addc_u32 s5, s5, 0
	s_cmp_ge_u32 s20, s89
	s_mov_b32 s6, s20
	s_cbranch_scc0 .LBB0_265
